# k3: gMLP workgroups join the next-layer w_in/w_out conversion (208 workers instead of 144)
# speedup vs baseline: 1.0635x; 1.0635x over previous
; template <bool COOP>
; __global__ void __launch_bounds__(NTHREADS, 2) mega(Params p0) {
;     ...
;                     if (G == 256 && l + 1 < DEPTH && !(ph0 & 1) && b0 >= 64) convert_layer(p, lt, l + 1, 0, 864, b0 - 64, nat - 64, (float*)lds);
.LBB0_228:
	v_readlane_b32 s0, v253, 52
	v_readlane_b32 s1, v253, 53
	s_andn2_b64 vcc, exec, s[0:1]
	s_cbranch_vccnz .LBB0_259
	s_cmp_gt_i32 s60, 27
	s_cselect_b64 s[0:1], -1, 0
	s_cmpk_lt_i32 s86, 0x30
	s_cselect_b64 s[4:5], -1, 0
	s_or_b64 s[0:1], s[0:1], s[4:5]
	s_and_b64 vcc, exec, s[0:1]
	s_cbranch_vccnz .LBB0_259
	v_readlane_b32 s37, v254, 1
	s_add_i32 s37, s37, 1
	s_add_i32 s34, s86, 0xffffffd0
	s_movk_i32 s35, 0x360
	s_movk_i32 s36, 0xd0
	s_mov_b32 s38, 2
	s_branch .Lconv_entry
